# norm phases (3/16): rms_row loop with gain loaded once per wave, all 8 row loads in flight together, no waits on stores
# speedup vs baseline: 1.0088x; 1.0043x over previous
; #define INP(i) ((const float*)ldp(tab, (i)))
; __device__ __forceinline__ void rms_row(const float* xr, const float* gain, bf16_t* o, int lane) {
;     const f32x4* x4 = (const f32x4*)xr + lane; const f32x4* g4 = (const f32x4*)gain + lane;
;     f32x4 v[8]; float s = 0.f;
; #pragma unroll
;     for (int j = 0; j < 8; ++j) { v[j] = x4[64 * j]; s += (v[j].x * v[j].x + v[j].y * v[j].y) + (v[j].z * v[j].z + v[j].w * v[j].w); }
; __global__ void __launch_bounds__(512, 2) mega(Args a) {
;     ...
;         }
;         else if (kind == 3) {
;             const float* gain = INP(f ? I_F2N : I_MIXN);
;             for (int prep_ = 0; prep_ < PROBE_NORM; ++prep_) for (int m = gw; m < MTOK; m += NGW) rms_row(OUTP + (size_t)m * DM, gain, H + (size_t)m * DM, lane);
;         }
.LBB0_655:
	s_andn2_b64 vcc, exec, s[0:1]
	s_cbranch_vccnz .LBB0_1027
	s_add_u32 s0, s68, 0x15c00000
	s_addc_u32 s1, s69, 0
	v_readlane_b32 s2, v254, 54
	s_cmp_lt_i32 s2, 2
	s_mov_b64 s[4:5], -1
	s_cbranch_scc1 .LBB0_698
	v_readlane_b32 s2, v254, 54
	s_cmp_gt_i32 s2, 2
	s_cbranch_scc0 .LBB0_662
	v_readlane_b32 s2, v254, 33
	s_lshl_b32 s2, s2, 3
	s_add_i32 s2, s2, 0
	s_add_i32 s2, s2, 0x20000
	v_mov_b32_e32 v0, s2
	ds_read_b64 v[0:1], v0
	s_cmpk_gt_i32 s62, 0x3fff
	s_waitcnt lgkmcnt(0)
	v_readfirstlane_b32 s5, v1
	v_readfirstlane_b32 s4, v0
	s_cbranch_scc1 .LBB0_661
	v_lshlrev_b32_e32 v0, 4, v204
	v_mov_b32_e32 v1, v64
	v_lshl_add_u64 v[36:37], s[4:5], 0, v[0:1]
	s_mov_b64 s[2:3], 0x1400
	v_lshl_add_u64 v[40:41], v[36:37], 0, s[2:3]
	s_mov_b64 s[2:3], 0x1800
	s_ashr_i32 s63, s62, 31
	v_lshl_add_u64 v[42:43], v[36:37], 0, s[2:3]
	s_lshl_b64 s[2:3], s[62:63], 12
	s_add_u32 s2, s68, s2
	v_lshlrev_b32_e32 v2, 3, v204
	v_mov_b32_e32 v3, v64
	s_addc_u32 s3, s69, s3
	v_lshl_add_u64 v[2:3], s[2:3], 0, v[2:3]
	s_mov_b64 s[2:3], 0x9a00e00
	s_ashr_i32 s65, s64, 31
	v_lshl_add_u64 v[46:47], v[2:3], 0, s[2:3]
	s_lshl_b64 s[4:5], s[64:65], 12
	s_lshl_b64 s[2:3], s[62:63], 13
	v_readlane_b32 s8, v254, 28
	v_readlane_b32 s9, v254, 29
	s_add_u32 s2, s8, s2
	s_addc_u32 s3, s9, s3
	s_mov_b64 s[6:7], 0x1c00
	v_lshl_add_u64 v[0:1], s[2:3], 0, v[0:1]
	v_lshl_add_u64 v[38:39], v[36:37], 0, s[94:95]
	v_lshl_add_u64 v[44:45], v[36:37], 0, s[6:7]
	v_lshl_add_u64 v[48:49], v[0:1], 0, s[6:7]
	s_lshl_b64 s[6:7], s[64:65], 13
	s_mov_b32 s3, s62
	global_load_dwordx4 v[72:75], v[36:37], off
	global_load_dwordx4 v[76:79], v[36:37], off offset:1024
	global_load_dwordx4 v[80:83], v[36:37], off offset:2048
	global_load_dwordx4 v[84:87], v[36:37], off offset:3072
	global_load_dwordx4 v[88:91], v[38:39], off
	global_load_dwordx4 v[92:95], v[40:41], off
	global_load_dwordx4 v[96:99], v[42:43], off
	global_load_dwordx4 v[100:103], v[44:45], off
; __device__ __forceinline__ unsigned cvt_pk_bf16(float lo, float hi) { unsigned r; asm volatile("v_cvt_pk_bf16_f32 %0, %1, %2" : "=v"(r) : "v"(lo), "v"(hi)); return r; }
; __device__ __forceinline__ float wave_sum(float x) { return x32sum(x16sum(sum16(x))); }
; __device__ __forceinline__ void rms_row(const float* xr, const float* gain, bf16_t* o, int lane) {
;     const f32x4* x4 = (const f32x4*)xr + lane; const f32x4* g4 = (const f32x4*)gain + lane;
;     f32x4 v[8]; float s = 0.f;
; #pragma unroll
;     for (int j = 0; j < 8; ++j) { v[j] = x4[64 * j]; s += (v[j].x * v[j].x + v[j].y * v[j].y) + (v[j].z * v[j].z + v[j].w * v[j].w); }
;     const float r = __builtin_amdgcn_rsqf(wave_sum(s) * (1.0f / 2048.0f) + EPS);
;     u32x2* o2 = (u32x2*)o + lane;
; #pragma unroll
;     for (int j = 0; j < 8; ++j) { const f32x4 gg = g4[64 * j]; u32x2 w; w.x = cvt_pk_bf16(v[j].x * r * gg.x, v[j].y * r * gg.y); w.y = cvt_pk_bf16(v[j].z * r * gg.z, v[j].w * r * gg.w); o2[64 * j] = w; }
; }
.LBB0_660:
	v_add_co_u32_e32 v0, vcc, 0xfffff000, v48
	s_add_i32 s3, s3, s64
	s_nop 0
	v_addc_co_u32_e32 v1, vcc, -1, v49, vcc
	global_load_dwordx4 v[28:31], v[0:1], off offset:-3072
	global_load_dwordx4 v[16:19], v[0:1], off offset:-2048
	global_load_dwordx4 v[4:7], v[0:1], off offset:-1024
	global_load_dwordx4 v[108:111], v[48:49], off offset:-4096
	global_load_dwordx4 v[24:27], v[48:49], off offset:-3072
	global_load_dwordx4 v[20:23], v[48:49], off offset:-2048
	global_load_dwordx4 v[8:11], v[48:49], off offset:-1024
	global_load_dwordx4 v[12:15], v[48:49], off
	s_cmpk_gt_i32 s3, 0x3fff
	v_lshl_add_u64 v[48:49], v[48:49], 0, s[6:7]
	s_waitcnt vmcnt(0)
	v_mul_f32_e32 v104, v29, v29
	v_mul_f32_e32 v105, v31, v31
	v_fmac_f32_e32 v104, v28, v28
	v_fmac_f32_e32 v105, v30, v30
	v_add_f32_e32 v32, v104, v105
	v_mul_f32_e32 v104, v17, v17
	v_mul_f32_e32 v105, v19, v19
	v_fmac_f32_e32 v104, v16, v16
	v_fmac_f32_e32 v105, v18, v18
	v_add_f32_e32 v104, v104, v105
	v_add_f32_e32 v32, v32, v104
	v_mul_f32_e32 v104, v5, v5
	v_mul_f32_e32 v105, v7, v7
	v_fmac_f32_e32 v104, v4, v4
	v_fmac_f32_e32 v105, v6, v6
	v_add_f32_e32 v104, v104, v105
	v_add_f32_e32 v32, v32, v104
	v_mul_f32_e32 v104, v109, v109
	v_mul_f32_e32 v105, v111, v111
	v_fmac_f32_e32 v104, v108, v108
	v_fmac_f32_e32 v105, v110, v110
	v_add_f32_e32 v104, v104, v105
	v_add_f32_e32 v32, v32, v104
	v_mul_f32_e32 v104, v25, v25
	v_mul_f32_e32 v105, v27, v27
	v_fmac_f32_e32 v104, v24, v24
	v_fmac_f32_e32 v105, v26, v26
	v_add_f32_e32 v104, v104, v105
	v_add_f32_e32 v32, v32, v104
	v_mul_f32_e32 v104, v21, v21
	v_mul_f32_e32 v105, v23, v23
	v_fmac_f32_e32 v104, v20, v20
	v_fmac_f32_e32 v105, v22, v22
	v_add_f32_e32 v104, v104, v105
	v_add_f32_e32 v32, v32, v104
	v_mul_f32_e32 v104, v9, v9
	v_mul_f32_e32 v105, v11, v11
	v_fmac_f32_e32 v104, v8, v8
	v_fmac_f32_e32 v105, v10, v10
	v_add_f32_e32 v104, v104, v105
	v_add_f32_e32 v32, v32, v104
	v_mul_f32_e32 v104, v13, v13
	v_mul_f32_e32 v105, v15, v15
	v_fmac_f32_e32 v104, v12, v12
	v_fmac_f32_e32 v105, v14, v14
	v_add_f32_e32 v104, v104, v105
	v_add_f32_e32 v32, v32, v104
	s_nop 1
	v_add_f32_dpp v32, v32, v32 quad_perm:[1,0,3,2] row_mask:0xf bank_mask:0xf bound_ctrl:1
	s_nop 1
	v_add_f32_dpp v32, v32, v32 quad_perm:[2,3,0,1] row_mask:0xf bank_mask:0xf bound_ctrl:1
	s_nop 1
	v_add_f32_dpp v32, v32, v32 row_half_mirror row_mask:0xf bank_mask:0xf bound_ctrl:1
	s_nop 1
	v_add_f32_dpp v32, v32, v32 row_mirror row_mask:0xf bank_mask:0xf bound_ctrl:1
	v_mov_b32_e32 v33, v32
	s_nop 1
	v_permlane16_swap_b32_e32 v32, v33
	v_add_f32_e32 v32, v32, v33
	v_mov_b32_e32 v33, v32
	s_nop 1
	v_permlane32_swap_b32_e32 v32, v33
	v_add_f32_e32 v32, v32, v33
	v_fmamk_f32 v32, v32, 0x3a000000, v232
	v_rsq_f32_e32 v50, v32
	s_nop 0
	v_mul_f32_e32 v28, v28, v50
	v_mul_f32_e32 v29, v29, v50
	v_mul_f32_e32 v30, v30, v50
	v_mul_f32_e32 v31, v31, v50
	v_mul_f32_e32 v28, v72, v28
	v_mul_f32_e32 v29, v73, v29
	v_mul_f32_e32 v30, v74, v30
	v_mul_f32_e32 v31, v75, v31
	v_cvt_pk_bf16_f32 v112, v28, v29
	v_cvt_pk_bf16_f32 v113, v30, v31
	global_store_dwordx2 v[46:47], v[112:113], off offset:-3584
	v_mul_f32_e32 v16, v16, v50
	v_mul_f32_e32 v17, v17, v50
	v_mul_f32_e32 v18, v18, v50
	v_mul_f32_e32 v19, v19, v50
	v_mul_f32_e32 v16, v76, v16
	v_mul_f32_e32 v17, v77, v17
	v_mul_f32_e32 v18, v78, v18
	v_mul_f32_e32 v19, v79, v19
	v_cvt_pk_bf16_f32 v114, v16, v17
	v_cvt_pk_bf16_f32 v115, v18, v19
	global_store_dwordx2 v[46:47], v[114:115], off offset:-3072
	v_mul_f32_e32 v4, v4, v50
	v_mul_f32_e32 v5, v5, v50
	v_mul_f32_e32 v6, v6, v50
	v_mul_f32_e32 v7, v7, v50
	v_mul_f32_e32 v4, v80, v4
	v_mul_f32_e32 v5, v81, v5
	v_mul_f32_e32 v6, v82, v6
	v_mul_f32_e32 v7, v83, v7
	v_cvt_pk_bf16_f32 v112, v4, v5
	v_cvt_pk_bf16_f32 v113, v6, v7
	global_store_dwordx2 v[46:47], v[112:113], off offset:-2560
	v_mul_f32_e32 v108, v108, v50
	v_mul_f32_e32 v109, v109, v50
	v_mul_f32_e32 v110, v110, v50
	v_mul_f32_e32 v111, v111, v50
	v_mul_f32_e32 v108, v84, v108
	v_mul_f32_e32 v109, v85, v109
	v_mul_f32_e32 v110, v86, v110
	v_mul_f32_e32 v111, v87, v111
	v_cvt_pk_bf16_f32 v114, v108, v109
	v_cvt_pk_bf16_f32 v115, v110, v111
	global_store_dwordx2 v[46:47], v[114:115], off offset:-2048
	v_mul_f32_e32 v24, v24, v50
	v_mul_f32_e32 v25, v25, v50
	v_mul_f32_e32 v26, v26, v50
	v_mul_f32_e32 v27, v27, v50
	v_mul_f32_e32 v24, v88, v24
	v_mul_f32_e32 v25, v89, v25
	v_mul_f32_e32 v26, v90, v26
	v_mul_f32_e32 v27, v91, v27
	v_cvt_pk_bf16_f32 v112, v24, v25
	v_cvt_pk_bf16_f32 v113, v26, v27
	global_store_dwordx2 v[46:47], v[112:113], off offset:-1536
	v_mul_f32_e32 v20, v20, v50
	v_mul_f32_e32 v21, v21, v50
	v_mul_f32_e32 v22, v22, v50
	v_mul_f32_e32 v23, v23, v50
	v_mul_f32_e32 v20, v92, v20
	v_mul_f32_e32 v21, v93, v21
	v_mul_f32_e32 v22, v94, v22
	v_mul_f32_e32 v23, v95, v23
	v_cvt_pk_bf16_f32 v114, v20, v21
	v_cvt_pk_bf16_f32 v115, v22, v23
	global_store_dwordx2 v[46:47], v[114:115], off offset:-1024
	v_mul_f32_e32 v8, v8, v50
	v_mul_f32_e32 v9, v9, v50
	v_mul_f32_e32 v10, v10, v50
	v_mul_f32_e32 v11, v11, v50
	v_mul_f32_e32 v8, v96, v8
	v_mul_f32_e32 v9, v97, v9
	v_mul_f32_e32 v10, v98, v10
	v_mul_f32_e32 v11, v99, v11
	v_cvt_pk_bf16_f32 v112, v8, v9
	v_cvt_pk_bf16_f32 v113, v10, v11
	global_store_dwordx2 v[46:47], v[112:113], off offset:-512
	v_mul_f32_e32 v12, v12, v50
	v_mul_f32_e32 v13, v13, v50
	v_mul_f32_e32 v14, v14, v50
	v_mul_f32_e32 v15, v15, v50
	v_mul_f32_e32 v12, v100, v12
	v_mul_f32_e32 v13, v101, v13
	v_mul_f32_e32 v14, v102, v14
	v_mul_f32_e32 v15, v103, v15
	v_cvt_pk_bf16_f32 v114, v12, v13
	v_cvt_pk_bf16_f32 v115, v14, v15
	global_store_dwordx2 v[46:47], v[114:115], off
	v_lshl_add_u64 v[46:47], v[46:47], 0, s[4:5]
	s_cbranch_scc0 .LBB0_660
